# swiglu GEMM: row-scale sums staged in LDS during the first K iteration; epilogue reads them from LDS, no vmcnt(0) drain at epilogue start
# baseline (speedup 1.0000x reference)
; #define PG8_STAGE(bufoff, gbase, voff) do { _Pragma("unroll") for (int _i = 0; _i < 2; ++_i) \
;         __builtin_amdgcn_global_load_lds((const unsigned*)((const char*)(gbase) + (voff)[_i]), (LAS unsigned*)(lds + (bufoff) + ldsw + _i * 8192), 16, 0, 0); } while (0)
; #define PG8_LDA(dst, b, h) do { _Pragma("unroll") for (int m = 0; m < 4; ++m) _Pragma("unroll") for (int k = 0; k < 2; ++k) dst[m][k] = *(const LAS bf16x8*)(lds + PG8_SA(b, h) + aoff + m * 2048 + k * 1024); } while (0)
; #define PG8_LDB(dst, b, h) do { _Pragma("unroll") for (int n = 0; n < 2; ++n) _Pragma("unroll") for (int k = 0; k < 2; ++k) dst[n][k] = *(const LAS bf16x8*)(lds + PG8_SB(b, h) + boff + n * 2048 + k * 1024); } while (0)
; #define PG8_MMA(ai, bj, At, Bt) do { __builtin_amdgcn_s_setprio(1); _Pragma("unroll") for (int m = 0; m < 4; ++m) _Pragma("unroll") for (int n = 0; n < 2; ++n) _Pragma("unroll") for (int k = 0; k < 2; ++k) \
;         acc[ai][bj][m][n] = __builtin_amdgcn_mfma_f32_16x16x32_bf16(Bt[n][k], At[m][k], acc[ai][bj][m][n], 0, 0, 0); __builtin_amdgcn_s_setprio(0); } while (0)
; #define PG8_WAIT_V(n) asm volatile("s_waitcnt vmcnt(" #n ")" ::: "memory")
; #define PG8_WAIT_L(n) asm volatile("s_waitcnt lgkmcnt(" #n ")" ::: "memory")
; #define PG8_BAR __builtin_amdgcn_s_barrier()
; #define PG8_SCHED __builtin_amdgcn_sched_barrier(0)
; template <class Epi>
; DEVI void gemm_phase(LAS unsigned char* lds, const Gemm g, const Epi& E) {
;     ...
;             PG8_LDB(B0, 0, 0); PG8_SCHED; PG8_LDA(At, 0, 0); PG8_STAGE(PG8_SA(1, 1), a1 + hstepA, voffA);
;             PG8_WAIT_L(8); PG8_BAR; PG8_WAIT_L(0); PG8_MMA(0, 0, At, B0); PG8_BAR; PG8_SCHED;
;             PG8_LDB(B1, 0, 1); PG8_STAGE(PG8_SB(0, 0), b2, voffB);
;             PG8_BAR; PG8_WAIT_L(0); PG8_MMA(0, 1, At, B1); PG8_BAR;
;             PG8_LDA(At, 0, 1); PG8_STAGE(PG8_SA(0, 0), a2, voffA);
;             PG8_BAR; PG8_WAIT_L(0); PG8_MMA(1, 0, At, B0); PG8_BAR; PG8_SCHED;
;             PG8_STAGE(PG8_SB(0, 1), b2 + hstepB, voffB);
;             PG8_WAIT_V(6); PG8_BAR; PG8_MMA(1, 1, At, B1); PG8_BAR;
;     ...
;                 for (int i = 0; i < 8; ++i) q4[i] = *(const f32x4*)(E.ssq_in + (size_t)(row0 + (i >> 2) * HALF + (i & 3) * 16) * 4);
.LBB0_1672:
	s_add_u32 s26, s16, 0xfffc0080
	s_addc_u32 s27, s17, -1
	s_add_i32 s38, 0, 0x10000
	v_add_u32_e32 v142, s38, v197
	ds_read_b128 v[130:133], v142
	ds_read_b128 v[134:137], v142 offset:1024
	ds_read_b128 v[138:141], v142 offset:2048
	ds_read_b128 v[142:145], v142 offset:3072
	s_cmp_eq_u32 s19, 12
	s_cselect_b32 s47, s0, s27
	s_cselect_b32 s46, s1, s26
	s_cselect_b32 s37, s5, s18
	s_cselect_b32 s36, s7, s9
	v_lshl_add_u64 v[162:163], s[16:17], 0, v[152:153]
	s_add_i32 m0, s79, 0xc000
	ds_read_b128 v[178:181], v201
	ds_read_b128 v[182:185], v201 offset:1024
	ds_read_b128 v[186:189], v201 offset:2048
	ds_read_b128 v[202:205], v201 offset:3072
	ds_read_b128 v[206:209], v201 offset:4096
	ds_read_b128 v[214:217], v201 offset:5120
	ds_read_b128 v[218:221], v201 offset:6144
	ds_read_b128 v[222:225], v201 offset:7168
	global_load_lds_dwordx4 v[162:163], off
	v_lshl_add_u64 v[162:163], s[16:17], 0, v[176:177]
	s_add_i32 m0, s79, 0xe000
	s_nop 0
	global_load_lds_dwordx4 v[162:163], off
	s_waitcnt lgkmcnt(8)
	s_barrier
	s_cmp_lg_u32 s19, -2
	s_cbranch_scc1 .Lrsl_sw
	v_and_b32_e32 v248, 0xff, v154
	v_lshlrev_b32_e32 v248, 4, v248
	v_add_u32_e32 v249, 0x21000, v248
	v_lshl_add_u32 v248, s4, 12, v248
	global_load_dwordx4 v[244:247], v248, s[10:11]
.Lrsl_sw:
	s_waitcnt lgkmcnt(0)
	s_setprio 1
	s_waitcnt lgkmcnt(0)
	v_mfma_f32_16x16x32_bf16 v[126:129], v[130:133], v[178:181], v[126:129]
	v_mfma_f32_16x16x32_bf16 v[122:125], v[138:141], v[178:181], v[122:125]
	v_mfma_f32_16x16x32_bf16 v[110:113], v[130:133], v[186:189], v[110:113]
	v_mfma_f32_16x16x32_bf16 v[106:109], v[138:141], v[186:189], v[106:109]
	v_mfma_f32_16x16x32_bf16 v[94:97], v[130:133], v[206:209], v[94:97]
	v_mfma_f32_16x16x32_bf16 v[90:93], v[138:141], v[206:209], v[90:93]
	v_mfma_f32_16x16x32_bf16 v[78:81], v[130:133], v[218:221], v[78:81]
	v_mfma_f32_16x16x32_bf16 v[74:77], v[138:141], v[218:221], v[74:77]
	v_mfma_f32_16x16x32_bf16 v[126:129], v[134:137], v[182:185], v[126:129]
	v_mfma_f32_16x16x32_bf16 v[122:125], v[142:145], v[182:185], v[122:125]
	v_mfma_f32_16x16x32_bf16 v[110:113], v[134:137], v[202:205], v[110:113]
	v_mfma_f32_16x16x32_bf16 v[106:109], v[142:145], v[202:205], v[106:109]
	v_mfma_f32_16x16x32_bf16 v[94:97], v[134:137], v[214:217], v[94:97]
	v_mfma_f32_16x16x32_bf16 v[90:93], v[142:145], v[214:217], v[90:93]
	v_mfma_f32_16x16x32_bf16 v[78:81], v[134:137], v[222:225], v[78:81]
	v_mfma_f32_16x16x32_bf16 v[74:77], v[142:145], v[222:225], v[74:77]
	s_setprio 0
	s_barrier
	s_add_i32 s39, 0, 0x14000
	v_add_u32_e32 v162, s39, v197
	s_add_i32 s26, s38, s78
	ds_read_b128 v[226:229], v162
	ds_read_b128 v[230:233], v162 offset:1024
	ds_read_b128 v[234:237], v162 offset:2048
	ds_read_b128 v[238:241], v162 offset:3072
	v_lshl_add_u64 v[162:163], s[36:37], 0, v[8:9]
	s_mov_b32 m0, s26
	v_lshl_add_u64 v[164:165], s[36:37], 0, v[146:147]
	global_load_lds_dwordx4 v[162:163], off
	s_add_i32 m0, s26, 0x2000
	s_nop 0
	global_load_lds_dwordx4 v[164:165], off
	s_barrier
	s_waitcnt lgkmcnt(0)
	s_setprio 1
	s_waitcnt lgkmcnt(0)
	v_mfma_f32_16x16x32_bf16 v[118:121], v[226:229], v[178:181], v[118:121]
	v_mfma_f32_16x16x32_bf16 v[114:117], v[234:237], v[178:181], v[114:117]
	v_mfma_f32_16x16x32_bf16 v[102:105], v[226:229], v[186:189], v[102:105]
	v_mfma_f32_16x16x32_bf16 v[98:101], v[234:237], v[186:189], v[98:101]
	v_mfma_f32_16x16x32_bf16 v[86:89], v[226:229], v[206:209], v[86:89]
	v_mfma_f32_16x16x32_bf16 v[82:85], v[234:237], v[206:209], v[82:85]
	v_mfma_f32_16x16x32_bf16 v[70:73], v[226:229], v[218:221], v[70:73]
	v_mfma_f32_16x16x32_bf16 v[66:69], v[234:237], v[218:221], v[66:69]
	v_mfma_f32_16x16x32_bf16 v[118:121], v[230:233], v[182:185], v[118:121]
	v_mfma_f32_16x16x32_bf16 v[114:117], v[238:241], v[182:185], v[114:117]
	v_mfma_f32_16x16x32_bf16 v[102:105], v[230:233], v[202:205], v[102:105]
	v_mfma_f32_16x16x32_bf16 v[98:101], v[238:241], v[202:205], v[98:101]
	v_mfma_f32_16x16x32_bf16 v[86:89], v[230:233], v[214:217], v[86:89]
	v_mfma_f32_16x16x32_bf16 v[82:85], v[238:241], v[214:217], v[82:85]
	v_mfma_f32_16x16x32_bf16 v[70:73], v[230:233], v[222:225], v[70:73]
	v_mfma_f32_16x16x32_bf16 v[66:69], v[238:241], v[222:225], v[66:69]
	s_setprio 0
	s_mov_b32 m0, s79
	v_lshl_add_u64 v[190:191], s[46:47], 0, v[150:151]
	s_barrier
	ds_read_b128 v[178:181], v201 offset:16384
	ds_read_b128 v[182:185], v201 offset:17408
	ds_read_b128 v[186:189], v201 offset:18432
	ds_read_b128 v[202:205], v201 offset:19456
	ds_read_b128 v[206:209], v201 offset:20480
	ds_read_b128 v[214:217], v201 offset:21504
	ds_read_b128 v[218:221], v201 offset:22528
	ds_read_b128 v[222:225], v201 offset:23552
	global_load_lds_dwordx4 v[190:191], off
	v_lshl_add_u64 v[194:195], s[46:47], 0, v[148:149]
	s_mov_b32 m0, s80
	s_nop 0
	global_load_lds_dwordx4 v[194:195], off
	s_barrier
	s_waitcnt lgkmcnt(0)
	s_setprio 1
	s_waitcnt lgkmcnt(0)
	v_mfma_f32_16x16x32_bf16 v[50:53], v[130:133], v[178:181], v[50:53]
	v_mfma_f32_16x16x32_bf16 v[54:57], v[138:141], v[178:181], v[54:57]
	v_mfma_f32_16x16x32_bf16 v[34:37], v[130:133], v[186:189], v[34:37]
	v_mfma_f32_16x16x32_bf16 v[38:41], v[138:141], v[186:189], v[38:41]
	v_mfma_f32_16x16x32_bf16 v[18:21], v[130:133], v[206:209], v[18:21]
	v_mfma_f32_16x16x32_bf16 v[22:25], v[138:141], v[206:209], v[22:25]
	v_mfma_f32_16x16x32_bf16 v[0:3], v[130:133], v[218:221], v[0:3]
	v_mfma_f32_16x16x32_bf16 v[4:7], v[138:141], v[218:221], v[4:7]
	v_mfma_f32_16x16x32_bf16 v[50:53], v[134:137], v[182:185], v[50:53]
	v_mfma_f32_16x16x32_bf16 v[54:57], v[142:145], v[182:185], v[54:57]
	v_mfma_f32_16x16x32_bf16 v[34:37], v[134:137], v[202:205], v[34:37]
	v_mfma_f32_16x16x32_bf16 v[38:41], v[142:145], v[202:205], v[38:41]
	v_mfma_f32_16x16x32_bf16 v[18:21], v[134:137], v[214:217], v[18:21]
	v_mfma_f32_16x16x32_bf16 v[22:25], v[142:145], v[214:217], v[22:25]
	v_mfma_f32_16x16x32_bf16 v[0:3], v[134:137], v[222:225], v[0:3]
	v_mfma_f32_16x16x32_bf16 v[4:7], v[142:145], v[222:225], v[4:7]
	s_setprio 0
	s_barrier
	s_add_u32 s26, s36, 0x40000
	s_addc_u32 s27, s37, 0
	s_add_i32 s38, s39, s78
	v_lshl_add_u64 v[130:131], s[26:27], 0, v[8:9]
	s_mov_b32 m0, s38
	s_nop 0
	global_load_lds_dwordx4 v[130:131], off
	v_lshl_add_u64 v[130:131], s[26:27], 0, v[146:147]
	s_add_i32 m0, s38, 0x2000
	s_nop 0
	global_load_lds_dwordx4 v[130:131], off
	s_waitcnt vmcnt(6)
	s_barrier
	s_cmp_lg_u32 s19, -2
	s_cbranch_scc1 .Lrsw_sw
	ds_write_b128 v249, v[244:247]
; #define PG8_STAGE(bufoff, gbase, voff) do { _Pragma("unroll") for (int _i = 0; _i < 2; ++_i) \
;         __builtin_amdgcn_global_load_lds((const unsigned*)((const char*)(gbase) + (voff)[_i]), (LAS unsigned*)(lds + (bufoff) + ldsw + _i * 8192), 16, 0, 0); } while (0)
; #define PG8_LDA(dst, b, h) do { _Pragma("unroll") for (int m = 0; m < 4; ++m) _Pragma("unroll") for (int k = 0; k < 2; ++k) dst[m][k] = *(const LAS bf16x8*)(lds + PG8_SA(b, h) + aoff + m * 2048 + k * 1024); } while (0)
; #define PG8_LDB(dst, b, h) do { _Pragma("unroll") for (int n = 0; n < 2; ++n) _Pragma("unroll") for (int k = 0; k < 2; ++k) dst[n][k] = *(const LAS bf16x8*)(lds + PG8_SB(b, h) + boff + n * 2048 + k * 1024); } while (0)
; #define PG8_MMA(ai, bj, At, Bt) do { __builtin_amdgcn_s_setprio(1); _Pragma("unroll") for (int m = 0; m < 4; ++m) _Pragma("unroll") for (int n = 0; n < 2; ++n) _Pragma("unroll") for (int k = 0; k < 2; ++k) \
;         acc[ai][bj][m][n] = __builtin_amdgcn_mfma_f32_16x16x32_bf16(Bt[n][k], At[m][k], acc[ai][bj][m][n], 0, 0, 0); __builtin_amdgcn_s_setprio(0); } while (0)
; #define PG8_WAIT_V(n) asm volatile("s_waitcnt vmcnt(" #n ")" ::: "memory")
; #define PG8_WAIT_L(n) asm volatile("s_waitcnt lgkmcnt(" #n ")" ::: "memory")
; #define PG8_BAR __builtin_amdgcn_s_barrier()
; #define PG8_SCHED __builtin_amdgcn_sched_barrier(0)
; template <class Epi>
; DEVI void gemm_phase(LAS unsigned char* lds, const Gemm g, const Epi& E) {
;     ...
;             PG8_WAIT_V(6); PG8_BAR; PG8_MMA(1, 1, At, B1); PG8_BAR;
;             PG8_LDB(B0, 1, 0); PG8_SCHED; PG8_LDA(At, 1, 0); PG8_STAGE(PG8_SA(0, 1), a2 + hstepA, voffA);
;             PG8_WAIT_L(8); PG8_BAR; PG8_WAIT_L(0); PG8_MMA(0, 0, At, B0); PG8_BAR; PG8_SCHED;
;             PG8_LDB(B1, 1, 1); PG8_STAGE(PG8_SB(1, 0), b3, voffB);
;             PG8_BAR; PG8_WAIT_L(0); PG8_MMA(0, 1, At, B1); PG8_BAR;
;             PG8_LDA(At, 1, 1); PG8_STAGE(PG8_SA(1, 0), a3, voffA);
;             PG8_BAR; PG8_WAIT_L(0); PG8_MMA(1, 0, At, B0); PG8_BAR; PG8_SCHED;
.Lrsw_sw:
	s_setprio 1
	v_mfma_f32_16x16x32_bf16 v[58:61], v[226:229], v[178:181], v[58:61]
	v_mfma_f32_16x16x32_bf16 v[62:65], v[234:237], v[178:181], v[62:65]
	v_mfma_f32_16x16x32_bf16 v[42:45], v[226:229], v[186:189], v[42:45]
	v_mfma_f32_16x16x32_bf16 v[46:49], v[234:237], v[186:189], v[46:49]
	v_mfma_f32_16x16x32_bf16 v[26:29], v[226:229], v[206:209], v[26:29]
	v_mfma_f32_16x16x32_bf16 v[30:33], v[234:237], v[206:209], v[30:33]
	v_mfma_f32_16x16x32_bf16 v[10:13], v[226:229], v[218:221], v[10:13]
	v_mfma_f32_16x16x32_bf16 v[14:17], v[234:237], v[218:221], v[14:17]
	v_mfma_f32_16x16x32_bf16 v[58:61], v[230:233], v[182:185], v[58:61]
	v_mfma_f32_16x16x32_bf16 v[62:65], v[238:241], v[182:185], v[62:65]
	v_mfma_f32_16x16x32_bf16 v[42:45], v[230:233], v[202:205], v[42:45]
	v_mfma_f32_16x16x32_bf16 v[46:49], v[238:241], v[202:205], v[46:49]
	v_mfma_f32_16x16x32_bf16 v[26:29], v[230:233], v[214:217], v[26:29]
	v_mfma_f32_16x16x32_bf16 v[30:33], v[238:241], v[214:217], v[30:33]
	v_mfma_f32_16x16x32_bf16 v[10:13], v[230:233], v[222:225], v[10:13]
	v_mfma_f32_16x16x32_bf16 v[14:17], v[238:241], v[222:225], v[14:17]
	s_setprio 0
	s_add_i32 s38, 0, 0x18000
	v_add_u32_e32 v142, s38, v197
	s_barrier
	ds_read_b128 v[130:133], v142
	ds_read_b128 v[134:137], v142 offset:1024
	ds_read_b128 v[138:141], v142 offset:2048
	ds_read_b128 v[142:145], v142 offset:3072
	s_add_u32 s26, s46, 0x40000
	s_addc_u32 s27, s47, 0
	s_mov_b32 m0, s81
	v_lshl_add_u64 v[226:227], s[26:27], 0, v[150:151]
	ds_read_b128 v[178:181], v201 offset:32768
	ds_read_b128 v[182:185], v201 offset:33792
	ds_read_b128 v[186:189], v201 offset:34816
	ds_read_b128 v[202:205], v201 offset:35840
	ds_read_b128 v[206:209], v201 offset:36864
	ds_read_b128 v[214:217], v201 offset:37888
	ds_read_b128 v[218:221], v201 offset:38912
	ds_read_b128 v[222:225], v201 offset:39936
	global_load_lds_dwordx4 v[226:227], off
	v_lshl_add_u64 v[226:227], s[26:27], 0, v[148:149]
	s_mov_b32 m0, s82
	s_nop 0
	global_load_lds_dwordx4 v[226:227], off
	s_waitcnt lgkmcnt(8)
	s_barrier
	s_waitcnt lgkmcnt(0)
	s_setprio 1
	s_waitcnt lgkmcnt(0)
	v_mfma_f32_16x16x32_bf16 v[126:129], v[130:133], v[178:181], v[126:129]
	v_mfma_f32_16x16x32_bf16 v[122:125], v[138:141], v[178:181], v[122:125]
	v_mfma_f32_16x16x32_bf16 v[110:113], v[130:133], v[186:189], v[110:113]
	v_mfma_f32_16x16x32_bf16 v[106:109], v[138:141], v[186:189], v[106:109]
	v_mfma_f32_16x16x32_bf16 v[94:97], v[130:133], v[206:209], v[94:97]
	v_mfma_f32_16x16x32_bf16 v[90:93], v[138:141], v[206:209], v[90:93]
	v_mfma_f32_16x16x32_bf16 v[78:81], v[130:133], v[218:221], v[78:81]
	v_mfma_f32_16x16x32_bf16 v[74:77], v[138:141], v[218:221], v[74:77]
	v_mfma_f32_16x16x32_bf16 v[126:129], v[134:137], v[182:185], v[126:129]
	v_mfma_f32_16x16x32_bf16 v[122:125], v[142:145], v[182:185], v[122:125]
	v_mfma_f32_16x16x32_bf16 v[110:113], v[134:137], v[202:205], v[110:113]
	v_mfma_f32_16x16x32_bf16 v[106:109], v[142:145], v[202:205], v[106:109]
	v_mfma_f32_16x16x32_bf16 v[94:97], v[134:137], v[214:217], v[94:97]
	v_mfma_f32_16x16x32_bf16 v[90:93], v[142:145], v[214:217], v[90:93]
	v_mfma_f32_16x16x32_bf16 v[78:81], v[134:137], v[222:225], v[78:81]
	v_mfma_f32_16x16x32_bf16 v[74:77], v[142:145], v[222:225], v[74:77]
	s_setprio 0
	s_barrier
	s_add_i32 s39, 0, 0x1c000
	s_add_i32 s26, s38, s78
	v_add_u32_e32 v192, s39, v197
	v_lshl_add_u64 v[162:163], v[162:163], 0, s[70:71]
	s_mov_b32 m0, s26
	ds_read_b128 v[226:229], v192
	ds_read_b128 v[230:233], v192 offset:1024
	ds_read_b128 v[234:237], v192 offset:2048
	ds_read_b128 v[238:241], v192 offset:3072
	global_load_lds_dwordx4 v[162:163], off
	v_lshl_add_u64 v[162:163], v[164:165], 0, s[70:71]
	s_add_i32 m0, s26, 0x2000
	s_nop 0
	global_load_lds_dwordx4 v[162:163], off
	s_barrier
	s_waitcnt lgkmcnt(0)
	s_setprio 1
	s_waitcnt lgkmcnt(0)
	v_mfma_f32_16x16x32_bf16 v[118:121], v[226:229], v[178:181], v[118:121]
	v_mfma_f32_16x16x32_bf16 v[114:117], v[234:237], v[178:181], v[114:117]
	v_mfma_f32_16x16x32_bf16 v[102:105], v[226:229], v[186:189], v[102:105]
	v_mfma_f32_16x16x32_bf16 v[98:101], v[234:237], v[186:189], v[98:101]
	v_mfma_f32_16x16x32_bf16 v[86:89], v[226:229], v[206:209], v[86:89]
	v_mfma_f32_16x16x32_bf16 v[82:85], v[234:237], v[206:209], v[82:85]
	v_mfma_f32_16x16x32_bf16 v[70:73], v[226:229], v[218:221], v[70:73]
	v_mfma_f32_16x16x32_bf16 v[66:69], v[234:237], v[218:221], v[66:69]
	v_mfma_f32_16x16x32_bf16 v[118:121], v[230:233], v[182:185], v[118:121]
	v_mfma_f32_16x16x32_bf16 v[114:117], v[238:241], v[182:185], v[114:117]
	v_mfma_f32_16x16x32_bf16 v[102:105], v[230:233], v[202:205], v[102:105]
	v_mfma_f32_16x16x32_bf16 v[98:101], v[238:241], v[202:205], v[98:101]
	v_mfma_f32_16x16x32_bf16 v[86:89], v[230:233], v[214:217], v[86:89]
	v_mfma_f32_16x16x32_bf16 v[82:85], v[238:241], v[214:217], v[82:85]
	v_mfma_f32_16x16x32_bf16 v[70:73], v[230:233], v[222:225], v[70:73]
	v_mfma_f32_16x16x32_bf16 v[66:69], v[238:241], v[222:225], v[66:69]
	s_setprio 0
	s_mov_b32 m0, s83
	v_lshl_add_u64 v[162:163], v[190:191], 0, s[70:71]
	s_barrier
	ds_read_b128 v[178:181], v201 offset:49152
	ds_read_b128 v[182:185], v201 offset:50176
	ds_read_b128 v[186:189], v201 offset:51200
	ds_read_b128 v[202:205], v201 offset:52224
	ds_read_b128 v[206:209], v201 offset:53248
	ds_read_b128 v[214:217], v201 offset:54272
	ds_read_b128 v[218:221], v201 offset:55296
	ds_read_b128 v[222:225], v201 offset:56320
	global_load_lds_dwordx4 v[162:163], off
	v_lshl_add_u64 v[162:163], v[194:195], 0, s[70:71]
	s_mov_b32 m0, s84
	s_nop 0
	global_load_lds_dwordx4 v[162:163], off
	s_barrier
; #define PG8_STAGE(bufoff, gbase, voff) do { _Pragma("unroll") for (int _i = 0; _i < 2; ++_i) \
;         __builtin_amdgcn_global_load_lds((const unsigned*)((const char*)(gbase) + (voff)[_i]), (LAS unsigned*)(lds + (bufoff) + ldsw + _i * 8192), 16, 0, 0); } while (0)
; #define PG8_MMA(ai, bj, At, Bt) do { __builtin_amdgcn_s_setprio(1); _Pragma("unroll") for (int m = 0; m < 4; ++m) _Pragma("unroll") for (int n = 0; n < 2; ++n) _Pragma("unroll") for (int k = 0; k < 2; ++k) \
;         acc[ai][bj][m][n] = __builtin_amdgcn_mfma_f32_16x16x32_bf16(Bt[n][k], At[m][k], acc[ai][bj][m][n], 0, 0, 0); __builtin_amdgcn_s_setprio(0); } while (0)
; #define PG8_WAIT_V(n) asm volatile("s_waitcnt vmcnt(" #n ")" ::: "memory")
; #define PG8_WAIT_L(n) asm volatile("s_waitcnt lgkmcnt(" #n ")" ::: "memory")
; #define PG8_BAR __builtin_amdgcn_s_barrier()
; #define PG8_SCHED __builtin_amdgcn_sched_barrier(0)
; template <class Epi>
; DEVI void gemm_phase(LAS unsigned char* lds, const Gemm g, const Epi& E) {
;     ...
;             PG8_BAR; PG8_WAIT_L(0); PG8_MMA(1, 0, At, B0); PG8_BAR; PG8_SCHED;
;             PG8_STAGE(PG8_SB(1, 1), b3 + hstepB, voffB);
;             PG8_WAIT_V(6); PG8_BAR; PG8_MMA(1, 1, At, B1); PG8_BAR;
;         }
;         {
;             const int row0 = cur.pm * BM + wr * 64 + fr, col0 = cur.pn * BM + wc * 32 + (Epi::PERM ? 8 : 4) * fq; constexpr int NST = Epi::PERM ? 4 : 16;
;             float rsv[8];
;             if constexpr (Epi::RS) { f32x4 q4[8];
; #pragma unroll
;                 for (int i = 0; i < 8; ++i) q4[i] = *(const f32x4*)(E.ssq_in + (size_t)(row0 + (i >> 2) * HALF + (i & 3) * 16) * 4);
; #pragma unroll
;                 for (int i = 0; i < 8; ++i) rsv[i] = rsqrtf((((q4[i][0] + q4[i][1]) + q4[i][2]) + q4[i][3]) * (1.f / DM) + 1e-6f); }
	s_waitcnt lgkmcnt(0)
	s_setprio 1
	s_waitcnt lgkmcnt(0)
	v_mfma_f32_16x16x32_bf16 v[50:53], v[130:133], v[178:181], v[50:53]
	v_mfma_f32_16x16x32_bf16 v[54:57], v[138:141], v[178:181], v[54:57]
	v_mfma_f32_16x16x32_bf16 v[34:37], v[130:133], v[186:189], v[34:37]
	v_mfma_f32_16x16x32_bf16 v[38:41], v[138:141], v[186:189], v[38:41]
	v_mfma_f32_16x16x32_bf16 v[18:21], v[130:133], v[206:209], v[18:21]
	v_mfma_f32_16x16x32_bf16 v[22:25], v[138:141], v[206:209], v[22:25]
	v_mfma_f32_16x16x32_bf16 v[0:3], v[130:133], v[218:221], v[0:3]
	v_mfma_f32_16x16x32_bf16 v[4:7], v[138:141], v[218:221], v[4:7]
	v_mfma_f32_16x16x32_bf16 v[50:53], v[134:137], v[182:185], v[50:53]
	v_mfma_f32_16x16x32_bf16 v[54:57], v[142:145], v[182:185], v[54:57]
	v_mfma_f32_16x16x32_bf16 v[34:37], v[134:137], v[202:205], v[34:37]
	v_mfma_f32_16x16x32_bf16 v[38:41], v[142:145], v[202:205], v[38:41]
	v_mfma_f32_16x16x32_bf16 v[18:21], v[134:137], v[214:217], v[18:21]
	v_mfma_f32_16x16x32_bf16 v[22:25], v[142:145], v[214:217], v[22:25]
	v_mfma_f32_16x16x32_bf16 v[0:3], v[134:137], v[222:225], v[0:3]
	v_mfma_f32_16x16x32_bf16 v[4:7], v[142:145], v[222:225], v[4:7]
	s_setprio 0
	s_barrier
	s_add_u32 s26, s36, 0x40080
	s_addc_u32 s27, s37, 0
	s_add_i32 s36, s39, s78
	v_lshl_add_u64 v[130:131], s[26:27], 0, v[8:9]
	s_mov_b32 m0, s36
	s_nop 0
	global_load_lds_dwordx4 v[130:131], off
	v_lshl_add_u64 v[130:131], s[26:27], 0, v[146:147]
	s_add_i32 m0, s36, 0x2000
	s_nop 0
	global_load_lds_dwordx4 v[130:131], off
	s_waitcnt vmcnt(6)
	s_barrier
	s_setprio 1
	v_mfma_f32_16x16x32_bf16 v[58:61], v[226:229], v[178:181], v[58:61]
	v_mfma_f32_16x16x32_bf16 v[62:65], v[234:237], v[178:181], v[62:65]
	v_mfma_f32_16x16x32_bf16 v[42:45], v[226:229], v[186:189], v[42:45]
	v_mfma_f32_16x16x32_bf16 v[46:49], v[234:237], v[186:189], v[46:49]
	v_mfma_f32_16x16x32_bf16 v[26:29], v[226:229], v[206:209], v[26:29]
	v_mfma_f32_16x16x32_bf16 v[30:33], v[234:237], v[206:209], v[30:33]
	v_mfma_f32_16x16x32_bf16 v[10:13], v[226:229], v[218:221], v[10:13]
	v_mfma_f32_16x16x32_bf16 v[14:17], v[234:237], v[218:221], v[14:17]
	v_mfma_f32_16x16x32_bf16 v[58:61], v[230:233], v[182:185], v[58:61]
	v_mfma_f32_16x16x32_bf16 v[62:65], v[238:241], v[182:185], v[62:65]
	v_mfma_f32_16x16x32_bf16 v[42:45], v[230:233], v[202:205], v[42:45]
	v_mfma_f32_16x16x32_bf16 v[46:49], v[238:241], v[202:205], v[46:49]
	v_mfma_f32_16x16x32_bf16 v[26:29], v[230:233], v[214:217], v[26:29]
	v_mfma_f32_16x16x32_bf16 v[30:33], v[238:241], v[214:217], v[30:33]
	v_mfma_f32_16x16x32_bf16 v[10:13], v[230:233], v[222:225], v[10:13]
	v_mfma_f32_16x16x32_bf16 v[14:17], v[238:241], v[222:225], v[14:17]
	s_setprio 0
	s_add_i32 s19, s19, 2
	s_add_u32 s16, s16, 0x100
	s_addc_u32 s17, s17, 0
	s_add_u32 s9, s9, 0x100
	s_addc_u32 s18, s18, 0
	s_cmp_gt_u32 s19, 13
	s_barrier
	s_cbranch_scc0 .LBB0_1672
	v_lshlrev_b32_e32 v213, 4, v193
	v_add_u32_e32 v213, 0x21000, v213
	v_lshl_add_u32 v194, s4, 8, v193
	v_add_u32_e32 v178, 0xb0, v194
	v_ashrrev_i32_e32 v195, 31, v194
	v_or_b32_e32 v190, 16, v194
	v_ashrrev_i32_e32 v179, 31, v178
	v_lshl_add_u64 v[130:131], v[194:195], 4, s[10:11]
	v_ashrrev_i32_e32 v191, 31, v190
	v_lshl_add_u64 v[134:135], v[178:179], 4, s[10:11]
	ds_read_b128 v[202:205], v213
	v_or_b32_e32 v188, 32, v194
	ds_read_b128 v[134:137], v213 offset:2816
	v_lshl_add_u64 v[130:131], v[190:191], 4, s[10:11]
	ds_read_b128 v[206:209], v213 offset:256
	v_ashrrev_i32_e32 v189, 31, v188
	v_or_b32_e32 v186, 48, v194
	v_lshl_add_u64 v[130:131], v[188:189], 4, s[10:11]
	v_ashrrev_i32_e32 v187, 31, v186
	ds_read_b128 v[214:217], v213 offset:512
	v_lshl_add_u64 v[130:131], v[186:187], 4, s[10:11]
	ds_read_b128 v[218:221], v213 offset:768
	v_add_u32_e32 v184, 0x80, v194
	v_ashrrev_i32_e32 v185, 31, v184
	v_add_u32_e32 v182, 0x90, v194
	v_lshl_add_u64 v[130:131], v[184:185], 4, s[10:11]
	v_ashrrev_i32_e32 v183, 31, v182
	ds_read_b128 v[138:141], v213 offset:2048
	v_lshl_add_u64 v[130:131], v[182:183], 4, s[10:11]
	v_add_u32_e32 v180, 0xa0, v194
	ds_read_b128 v[142:145], v213 offset:2304
	v_ashrrev_i32_e32 v181, 31, v180
	v_lshl_add_u64 v[130:131], v[180:181], 4, s[10:11]
	ds_read_b128 v[130:133], v213 offset:2560
	s_mov_b32 s0, 0x358637bd
	s_mov_b64 s[36:37], s[14:15]
	s_mov_b64 s[16:17], s[12:13]
	s_waitcnt lgkmcnt(0)
; template <class Epi>
; DEVI void gemm_phase(LAS unsigned char* lds, const Gemm g, const Epi& E) {
;     ...
;             if constexpr (Epi::RS) { f32x4 q4[8];
; #pragma unroll
;                 for (int i = 0; i < 8; ++i) q4[i] = *(const f32x4*)(E.ssq_in + (size_t)(row0 + (i >> 2) * HALF + (i & 3) * 16) * 4);
; #pragma unroll
;                 for (int i = 0; i < 8; ++i) rsv[i] = rsqrtf((((q4[i][0] + q4[i][1]) + q4[i][2]) + q4[i][3]) * (1.f / DM) + 1e-6f); }
	v_mov_b32_e32 v163, v202
	v_mov_b32_e32 v165, v204
	v_mov_b32_e32 v162, v206
	v_mov_b32_e32 v202, v207
	v_pk_add_f32 v[162:163], v[162:163], v[202:203]
	v_mov_b32_e32 v164, v208
	v_pk_add_f32 v[162:163], v[164:165], v[162:163]
	v_mov_b32_e32 v204, v209
	v_pk_add_f32 v[162:163], v[204:205], v[162:163]
	v_mov_b64_e32 v[202:203], s[0:1]
	v_pk_fma_f32 v[162:163], v[162:163], s[72:73], v[202:203] op_sel_hi:[1,0,0]
	v_mov_b32_e32 v165, v216
	v_mul_f32_e32 v164, 0x4b800000, v163
	v_cmp_gt_f32_e64 s[4:5], s94, v163
	v_cmp_gt_f32_e32 vcc, s94, v162
	v_mov_b32_e32 v216, v221
	v_cndmask_b32_e64 v163, v163, v164, s[4:5]
	v_rsq_f32_e32 v163, v163
	s_nop 0
	v_mul_f32_e32 v164, 0x45800000, v163
	v_cndmask_b32_e64 v200, v163, v164, s[4:5]
	v_mul_f32_e32 v163, 0x4b800000, v162
	v_cndmask_b32_e32 v162, v162, v163, vcc
	v_rsq_f32_e32 v162, v162
	v_mov_b32_e32 v164, v220
	v_pk_mul_f32 v[126:127], v[126:127], v[200:201] op_sel_hi:[1,0]
	v_pk_mul_f32 v[122:123], v[122:123], v[200:201] op_sel_hi:[1,0]
	v_mul_f32_e32 v163, 0x45800000, v162
	v_cndmask_b32_e32 v198, v162, v163, vcc
	v_mov_b32_e32 v162, v218
	v_mov_b32_e32 v163, v214
	v_mov_b32_e32 v214, v219
	v_pk_add_f32 v[162:163], v[162:163], v[214:215]
	v_pk_mul_f32 v[118:119], v[118:119], v[200:201] op_sel_hi:[1,0]
	v_pk_add_f32 v[162:163], v[164:165], v[162:163]
	v_pk_mul_f32 v[124:125], v[124:125], v[200:201] op_sel_hi:[1,0]
	v_pk_add_f32 v[162:163], v[216:217], v[162:163]
	v_pk_mul_f32 v[114:115], v[114:115], v[200:201] op_sel_hi:[1,0]
	v_pk_fma_f32 v[162:163], v[162:163], s[72:73], v[202:203] op_sel_hi:[1,0,0]
	v_pk_mul_f32 v[128:129], v[128:129], v[200:201] op_sel_hi:[1,0]
	v_mul_f32_e32 v164, 0x4b800000, v163
	v_cmp_gt_f32_e64 s[4:5], s94, v163
	v_cmp_gt_f32_e32 vcc, s94, v162
	v_pk_mul_f32 v[120:121], v[120:121], v[200:201] op_sel_hi:[1,0]
	v_cndmask_b32_e64 v163, v163, v164, s[4:5]
	v_rsq_f32_e32 v163, v163
	v_pk_mul_f32 v[116:117], v[116:117], v[200:201] op_sel_hi:[1,0]
	v_pk_mul_f32 v[106:107], v[106:107], v[198:199] op_sel_hi:[1,0]
	v_pk_mul_f32 v[110:111], v[110:111], v[198:199] op_sel_hi:[1,0]
	v_mul_f32_e32 v164, 0x45800000, v163
	v_cndmask_b32_e64 v196, v163, v164, s[4:5]
	v_mul_f32_e32 v163, 0x4b800000, v162
	v_cndmask_b32_e32 v162, v162, v163, vcc
	v_rsq_f32_e32 v162, v162
	v_pk_mul_f32 v[102:103], v[102:103], v[198:199] op_sel_hi:[1,0]
	v_pk_mul_f32 v[108:109], v[108:109], v[198:199] op_sel_hi:[1,0]
	v_pk_mul_f32 v[98:99], v[98:99], v[198:199] op_sel_hi:[1,0]
	v_mul_f32_e32 v163, 0x45800000, v162
	v_cndmask_b32_e32 v192, v162, v163, vcc
	v_mov_b32_e32 v162, v142
	v_mov_b32_e32 v163, v138
	v_mov_b32_e32 v138, v143
	v_pk_add_f32 v[138:139], v[162:163], v[138:139]
	v_mov_b32_e32 v142, v144
	v_mov_b32_e32 v143, v140
	v_pk_add_f32 v[138:139], v[142:143], v[138:139]
	v_mov_b32_e32 v142, v134
	v_mov_b32_e32 v143, v130
	v_mov_b32_e32 v130, v135
	v_pk_add_f32 v[130:131], v[142:143], v[130:131]
	v_mov_b32_e32 v134, v136
	v_mov_b32_e32 v135, v132
	v_pk_add_f32 v[130:131], v[134:135], v[130:131]
	v_mov_b32_e32 v132, v137
	v_pk_add_f32 v[130:131], v[132:133], v[130:131]
	v_mul_f32_e32 v133, 0xbfb8aa3b, v126
	v_exp_f32_e32 v133, v133
	v_mov_b32_e32 v140, v145
	v_pk_add_f32 v[138:139], v[140:141], v[138:139]
	v_pk_fma_f32 v[130:131], v[130:131], s[72:73], v[202:203] op_sel_hi:[1,0,0]
	v_add_f32_e32 v133, 1.0, v133
	v_rcp_f32_e32 v136, v133
	v_mul_f32_e32 v133, 0xbfb8aa3b, v122
	v_exp_f32_e32 v133, v133
	v_pk_fma_f32 v[138:139], v[138:139], s[72:73], v[202:203] op_sel_hi:[1,0,0]
	v_mul_f32_e32 v132, 0x4b800000, v131
	v_mul_f32_e32 v140, 0x4b800000, v139
	v_add_f32_e32 v133, 1.0, v133
	v_rcp_f32_e32 v142, v133
	v_mul_f32_e32 v133, 0xbfb8aa3b, v127
	v_exp_f32_e32 v133, v133
	v_cmp_gt_f32_e64 s[4:5], s94, v139
	v_cmp_gt_f32_e32 vcc, s94, v138
	v_pk_mul_f32 v[112:113], v[112:113], v[198:199] op_sel_hi:[1,0]
	v_add_f32_e32 v133, 1.0, v133
	v_rcp_f32_e32 v137, v133
	v_cndmask_b32_e64 v139, v139, v140, s[4:5]
	v_rsq_f32_e32 v139, v139
	v_pk_mul_f32 v[104:105], v[104:105], v[198:199] op_sel_hi:[1,0]
	v_pk_mul_f32 v[126:127], v[126:127], v[136:137]
	v_pk_mul_f32 v[100:101], v[100:101], v[198:199] op_sel_hi:[1,0]
	v_pk_mul_f32 v[118:119], v[118:119], v[126:127]
	v_mul_f32_e32 v126, 0xbfb8aa3b, v123
	v_exp_f32_e32 v126, v126
	v_mul_f32_e32 v140, 0x45800000, v139
	v_cndmask_b32_e64 v140, v139, v140, s[4:5]
	v_mul_f32_e32 v139, 0x4b800000, v138
	v_add_f32_e32 v126, 1.0, v126
	v_rcp_f32_e32 v143, v126
	v_cmp_gt_f32_e64 s[4:5], s94, v131
	v_cndmask_b32_e32 v138, v138, v139, vcc
	v_rsq_f32_e32 v138, v138
	v_pk_mul_f32 v[122:123], v[122:123], v[142:143]
	v_cndmask_b32_e64 v131, v131, v132, s[4:5]
	v_pk_mul_f32 v[122:123], v[114:115], v[122:123]
	v_mul_f32_e32 v115, 0xbfb8aa3b, v124
	v_exp_f32_e32 v115, v115
	v_mul_f32_e32 v114, 0xbfb8aa3b, v128
	v_exp_f32_e32 v114, v114
	v_rsq_f32_e32 v131, v131
	v_add_f32_e32 v115, 1.0, v115
	v_rcp_f32_e32 v126, v115
	v_mul_f32_e32 v115, 0xbfb8aa3b, v129
	v_exp_f32_e32 v115, v115
	v_add_f32_e32 v114, 1.0, v114
	v_rcp_f32_e32 v114, v114
	v_mul_f32_e32 v139, 0x45800000, v138
	v_add_f32_e32 v115, 1.0, v115
	v_rcp_f32_e32 v115, v115
	v_mul_f32_e32 v132, 0x45800000, v131
	v_cndmask_b32_e32 v138, v138, v139, vcc
	v_cmp_gt_f32_e32 vcc, s94, v130
	v_pk_mul_f32 v[114:115], v[128:129], v[114:115]
	v_cndmask_b32_e64 v134, v131, v132, s[4:5]
	v_pk_mul_f32 v[120:121], v[120:121], v[114:115]
	v_mul_f32_e32 v114, 0xbfb8aa3b, v125
	v_exp_f32_e32 v114, v114
	v_mul_f32_e32 v131, 0x4b800000, v130
	v_cndmask_b32_e32 v130, v130, v131, vcc
	v_rsq_f32_e32 v130, v130
	v_add_f32_e32 v114, 1.0, v114
	v_rcp_f32_e32 v127, v114
	v_pk_mul_f32 v[90:91], v[90:91], v[196:197] op_sel_hi:[1,0]
	v_mul_f32_e32 v131, 0x45800000, v130
; template <class Epi>
; DEVI void gemm_phase(LAS unsigned char* lds, const Gemm g, const Epi& E) {
;     ...
;                 for (int mm = 0; mm < 2; ++mm) {
;                     const int m = m0 + mm;
;                     const int r = row0 + ai * HALF + m * 16; float rs = 1.f, part = 0.f;
;                     if constexpr (Epi::RS) rs = rsv[ai * 4 + m];
;                     if constexpr (Epi::PAIR) E.pair8(cur.b, r, cur.pn * HALF + wc * 32 + 8 * fq, acc[ai][0][m][0] * rs, acc[ai][0][m][1] * rs, acc[ai][1][m][0] * rs, acc[ai][1][m][1] * rs);
	v_cndmask_b32_e32 v132, v130, v131, vcc
	v_lshl_or_b32 v130, s86, 7, v199
	v_ashrrev_i32_e32 v131, 31, v130
	v_pk_mul_f32 v[114:115], v[124:125], v[126:127]
	v_lshl_add_u64 v[130:131], v[130:131], 1, s[28:29]
	v_pk_mul_f32 v[124:125], v[116:117], v[114:115]
	v_cvt_pk_bf16_f32 v114, v118, v119
	v_cvt_pk_bf16_f32 v115, v120, v121
	v_cvt_pk_bf16_f32 v116, v122, v123
	v_cvt_pk_bf16_f32 v117, v124, v125
	v_mad_i64_i32 v[118:119], s[0:1], v194, s35, v[130:131]
	global_store_dwordx4 v[118:119], v[114:117], off
	v_pk_mul_f32 v[94:95], v[94:95], v[196:197] op_sel_hi:[1,0]
	v_pk_mul_f32 v[86:87], v[86:87], v[196:197] op_sel_hi:[1,0]
	v_mul_f32_e32 v115, 0xbfb8aa3b, v106
	v_exp_f32_e32 v115, v115
	v_mul_f32_e32 v114, 0xbfb8aa3b, v110
	v_exp_f32_e32 v114, v114
	v_pk_mul_f32 v[92:93], v[92:93], v[196:197] op_sel_hi:[1,0]
	v_add_f32_e32 v115, 1.0, v115
	v_rcp_f32_e32 v116, v115
	v_mul_f32_e32 v115, 0xbfb8aa3b, v111
	v_exp_f32_e32 v115, v115
	v_add_f32_e32 v114, 1.0, v114
	v_rcp_f32_e32 v114, v114
	v_pk_mul_f32 v[82:83], v[82:83], v[196:197] op_sel_hi:[1,0]
	v_add_f32_e32 v115, 1.0, v115
	v_rcp_f32_e32 v115, v115
	v_pk_mul_f32 v[96:97], v[96:97], v[196:197] op_sel_hi:[1,0]
	v_pk_mul_f32 v[88:89], v[88:89], v[196:197] op_sel_hi:[1,0]
	v_pk_mul_f32 v[84:85], v[84:85], v[196:197] op_sel_hi:[1,0]
	v_pk_mul_f32 v[110:111], v[110:111], v[114:115]
	v_pk_mul_f32 v[74:75], v[74:75], v[192:193] op_sel_hi:[1,0]
	v_pk_mul_f32 v[102:103], v[102:103], v[110:111]
	v_mul_f32_e32 v110, 0xbfb8aa3b, v107
	v_exp_f32_e32 v110, v110
	v_pk_mul_f32 v[78:79], v[78:79], v[192:193] op_sel_hi:[1,0]
	v_pk_mul_f32 v[70:71], v[70:71], v[192:193] op_sel_hi:[1,0]
	v_pk_mul_f32 v[76:77], v[76:77], v[192:193] op_sel_hi:[1,0]
	v_add_f32_e32 v110, 1.0, v110
	v_rcp_f32_e32 v117, v110
	v_pk_mul_f32 v[66:67], v[66:67], v[192:193] op_sel_hi:[1,0]
	v_pk_mul_f32 v[80:81], v[80:81], v[192:193] op_sel_hi:[1,0]
	v_pk_mul_f32 v[72:73], v[72:73], v[192:193] op_sel_hi:[1,0]
	v_pk_mul_f32 v[106:107], v[106:107], v[116:117]
	v_pk_mul_f32 v[68:69], v[68:69], v[192:193] op_sel_hi:[1,0]
	v_pk_mul_f32 v[106:107], v[98:99], v[106:107]
	v_mul_f32_e32 v99, 0xbfb8aa3b, v108
	v_exp_f32_e32 v99, v99
	v_mul_f32_e32 v98, 0xbfb8aa3b, v112
	v_exp_f32_e32 v98, v98
	v_pk_mul_f32 v[54:55], v[54:55], v[140:141] op_sel_hi:[1,0]
	v_add_f32_e32 v99, 1.0, v99
	v_rcp_f32_e32 v110, v99
	v_mul_f32_e32 v99, 0xbfb8aa3b, v113
	v_exp_f32_e32 v99, v99
	v_add_f32_e32 v98, 1.0, v98
	v_rcp_f32_e32 v98, v98
	v_pk_mul_f32 v[50:51], v[50:51], v[140:141] op_sel_hi:[1,0]
	v_add_f32_e32 v99, 1.0, v99
	v_rcp_f32_e32 v99, v99
	v_pk_mul_f32 v[58:59], v[58:59], v[140:141] op_sel_hi:[1,0]
	v_pk_mul_f32 v[56:57], v[56:57], v[140:141] op_sel_hi:[1,0]
	v_pk_mul_f32 v[52:53], v[52:53], v[140:141] op_sel_hi:[1,0]
	v_pk_mul_f32 v[98:99], v[112:113], v[98:99]
	v_pk_mul_f32 v[62:63], v[62:63], v[140:141] op_sel_hi:[1,0]
	v_pk_mul_f32 v[104:105], v[104:105], v[98:99]
	v_mul_f32_e32 v98, 0xbfb8aa3b, v109
	v_exp_f32_e32 v98, v98
	v_pk_mul_f32 v[60:61], v[60:61], v[140:141] op_sel_hi:[1,0]
	v_pk_mul_f32 v[64:65], v[64:65], v[140:141] op_sel_hi:[1,0]
	v_pk_mul_f32 v[38:39], v[38:39], v[138:139] op_sel_hi:[1,0]
	v_add_f32_e32 v98, 1.0, v98
	v_rcp_f32_e32 v111, v98
	v_pk_mul_f32 v[34:35], v[34:35], v[138:139] op_sel_hi:[1,0]
	v_pk_mul_f32 v[42:43], v[42:43], v[138:139] op_sel_hi:[1,0]
	v_pk_mul_f32 v[40:41], v[40:41], v[138:139] op_sel_hi:[1,0]
	v_pk_mul_f32 v[98:99], v[108:109], v[110:111]
	v_pk_mul_f32 v[36:37], v[36:37], v[138:139] op_sel_hi:[1,0]
	v_pk_mul_f32 v[108:109], v[100:101], v[98:99]
	v_cvt_pk_bf16_f32 v98, v102, v103
	v_cvt_pk_bf16_f32 v99, v104, v105
	v_cvt_pk_bf16_f32 v100, v106, v107
	v_cvt_pk_bf16_f32 v101, v108, v109
	v_mad_i64_i32 v[102:103], s[0:1], v190, s35, v[130:131]
	global_store_dwordx4 v[102:103], v[98:101], off
	v_pk_mul_f32 v[46:47], v[46:47], v[138:139] op_sel_hi:[1,0]
	v_pk_mul_f32 v[44:45], v[44:45], v[138:139] op_sel_hi:[1,0]
	v_mul_f32_e32 v99, 0xbfb8aa3b, v90
	v_exp_f32_e32 v99, v99
	v_mul_f32_e32 v98, 0xbfb8aa3b, v94
	v_exp_f32_e32 v98, v98
	v_pk_mul_f32 v[48:49], v[48:49], v[138:139] op_sel_hi:[1,0]
	v_add_f32_e32 v99, 1.0, v99
	v_rcp_f32_e32 v100, v99
	v_mul_f32_e32 v99, 0xbfb8aa3b, v95
	v_exp_f32_e32 v99, v99
	v_add_f32_e32 v98, 1.0, v98
	v_rcp_f32_e32 v98, v98
	v_pk_mul_f32 v[22:23], v[22:23], v[134:135] op_sel_hi:[1,0]
	v_add_f32_e32 v99, 1.0, v99
	v_rcp_f32_e32 v99, v99
	v_pk_mul_f32 v[18:19], v[18:19], v[134:135] op_sel_hi:[1,0]
	v_pk_mul_f32 v[26:27], v[26:27], v[134:135] op_sel_hi:[1,0]
	v_pk_mul_f32 v[24:25], v[24:25], v[134:135] op_sel_hi:[1,0]
	v_pk_mul_f32 v[94:95], v[94:95], v[98:99]
	v_pk_mul_f32 v[20:21], v[20:21], v[134:135] op_sel_hi:[1,0]
	v_pk_mul_f32 v[86:87], v[86:87], v[94:95]
	v_mul_f32_e32 v94, 0xbfb8aa3b, v91
	v_exp_f32_e32 v94, v94
	v_pk_mul_f32 v[30:31], v[30:31], v[134:135] op_sel_hi:[1,0]
	v_pk_mul_f32 v[28:29], v[28:29], v[134:135] op_sel_hi:[1,0]
	v_pk_mul_f32 v[32:33], v[32:33], v[134:135] op_sel_hi:[1,0]
	v_add_f32_e32 v94, 1.0, v94
	v_rcp_f32_e32 v101, v94
	v_pk_mul_f32 v[4:5], v[4:5], v[132:133] op_sel_hi:[1,0]
	v_pk_mul_f32 v[0:1], v[0:1], v[132:133] op_sel_hi:[1,0]
	v_pk_mul_f32 v[10:11], v[10:11], v[132:133] op_sel_hi:[1,0]
	v_pk_mul_f32 v[90:91], v[90:91], v[100:101]
	v_pk_mul_f32 v[6:7], v[6:7], v[132:133] op_sel_hi:[1,0]
	v_pk_mul_f32 v[90:91], v[82:83], v[90:91]
	v_mul_f32_e32 v83, 0xbfb8aa3b, v92
	v_exp_f32_e32 v83, v83
	v_mul_f32_e32 v82, 0xbfb8aa3b, v96
	v_exp_f32_e32 v82, v82
	v_pk_mul_f32 v[2:3], v[2:3], v[132:133] op_sel_hi:[1,0]
	v_add_f32_e32 v83, 1.0, v83
	v_rcp_f32_e32 v94, v83
	v_mul_f32_e32 v83, 0xbfb8aa3b, v97
	v_exp_f32_e32 v83, v83
	v_add_f32_e32 v82, 1.0, v82
; template <class Epi>
; DEVI void gemm_phase(LAS unsigned char* lds, const Gemm g, const Epi& E) {
;     ...
;                     if constexpr (Epi::PAIR) E.pair8(cur.b, r, cur.pn * HALF + wc * 32 + 8 * fq, acc[ai][0][m][0] * rs, acc[ai][0][m][1] * rs, acc[ai][1][m][0] * rs, acc[ai][1][m][1] * rs);
	v_rcp_f32_e32 v82, v82
	v_pk_mul_f32 v[14:15], v[14:15], v[132:133] op_sel_hi:[1,0]
	v_add_f32_e32 v83, 1.0, v83
	v_rcp_f32_e32 v83, v83
	v_pk_mul_f32 v[12:13], v[12:13], v[132:133] op_sel_hi:[1,0]
	v_pk_mul_f32 v[16:17], v[16:17], v[132:133] op_sel_hi:[1,0]
	s_and_b64 vcc, exec, s[2:3]
	v_pk_mul_f32 v[82:83], v[96:97], v[82:83]
	s_mov_b32 s86, s8
	v_pk_mul_f32 v[88:89], v[88:89], v[82:83]
	v_mul_f32_e32 v82, 0xbfb8aa3b, v93
	v_exp_f32_e32 v82, v82
	s_mov_b32 s4, s6
	v_add_f32_e32 v82, 1.0, v82
	v_rcp_f32_e32 v95, v82
	s_nop 0
	v_pk_mul_f32 v[82:83], v[92:93], v[94:95]
	s_nop 0
	v_pk_mul_f32 v[92:93], v[84:85], v[82:83]
	v_cvt_pk_bf16_f32 v82, v86, v87
	v_cvt_pk_bf16_f32 v83, v88, v89
	v_cvt_pk_bf16_f32 v84, v90, v91
	v_cvt_pk_bf16_f32 v85, v92, v93
	v_mad_i64_i32 v[86:87], s[0:1], v188, s35, v[130:131]
	global_store_dwordx4 v[86:87], v[82:85], off
	s_nop 1
	v_mul_f32_e32 v83, 0xbfb8aa3b, v74
	v_exp_f32_e32 v83, v83
	v_mul_f32_e32 v82, 0xbfb8aa3b, v78
	v_exp_f32_e32 v82, v82
	v_add_f32_e32 v83, 1.0, v83
	v_rcp_f32_e32 v84, v83
	v_mul_f32_e32 v83, 0xbfb8aa3b, v79
	v_exp_f32_e32 v83, v83
	v_add_f32_e32 v82, 1.0, v82
	v_rcp_f32_e32 v82, v82
	v_add_f32_e32 v83, 1.0, v83
	v_rcp_f32_e32 v83, v83
	s_nop 0
	v_pk_mul_f32 v[78:79], v[78:79], v[82:83]
	s_nop 0
	v_pk_mul_f32 v[70:71], v[70:71], v[78:79]
	v_mul_f32_e32 v78, 0xbfb8aa3b, v75
	v_exp_f32_e32 v78, v78
	s_nop 0
	v_add_f32_e32 v78, 1.0, v78
	v_rcp_f32_e32 v85, v78
	s_nop 0
	v_pk_mul_f32 v[74:75], v[74:75], v[84:85]
	s_nop 0
	v_pk_mul_f32 v[74:75], v[66:67], v[74:75]
	v_mul_f32_e32 v67, 0xbfb8aa3b, v76
	v_exp_f32_e32 v67, v67
	v_mul_f32_e32 v66, 0xbfb8aa3b, v80
	v_exp_f32_e32 v66, v66
	v_add_f32_e32 v67, 1.0, v67
	v_rcp_f32_e32 v78, v67
	v_mul_f32_e32 v67, 0xbfb8aa3b, v81
	v_exp_f32_e32 v67, v67
	v_add_f32_e32 v66, 1.0, v66
	v_rcp_f32_e32 v66, v66
	v_add_f32_e32 v67, 1.0, v67
	v_rcp_f32_e32 v67, v67
	s_nop 0
	v_pk_mul_f32 v[66:67], v[80:81], v[66:67]
	s_nop 0
	v_pk_mul_f32 v[72:73], v[72:73], v[66:67]
	v_mul_f32_e32 v66, 0xbfb8aa3b, v77
	v_exp_f32_e32 v66, v66
	s_nop 0
	v_add_f32_e32 v66, 1.0, v66
	v_rcp_f32_e32 v79, v66
	s_nop 0
	v_pk_mul_f32 v[66:67], v[76:77], v[78:79]
	s_nop 0
	v_pk_mul_f32 v[76:77], v[68:69], v[66:67]
	v_cvt_pk_bf16_f32 v66, v70, v71
	v_cvt_pk_bf16_f32 v67, v72, v73
	v_cvt_pk_bf16_f32 v68, v74, v75
	v_cvt_pk_bf16_f32 v69, v76, v77
	v_mad_i64_i32 v[70:71], s[0:1], v186, s35, v[130:131]
	global_store_dwordx4 v[70:71], v[66:69], off
	s_nop 1
	v_mul_f32_e32 v67, 0xbfb8aa3b, v54
	v_exp_f32_e32 v67, v67
	v_mul_f32_e32 v66, 0xbfb8aa3b, v50
	v_exp_f32_e32 v66, v66
	v_add_f32_e32 v67, 1.0, v67
	v_rcp_f32_e32 v68, v67
	v_mul_f32_e32 v67, 0xbfb8aa3b, v51
	v_exp_f32_e32 v67, v67
	v_add_f32_e32 v66, 1.0, v66
	v_rcp_f32_e32 v66, v66
	v_add_f32_e32 v67, 1.0, v67
	v_rcp_f32_e32 v67, v67
	s_nop 0
	v_pk_mul_f32 v[50:51], v[50:51], v[66:67]
	s_nop 0
	v_pk_mul_f32 v[50:51], v[58:59], v[50:51]
	v_mul_f32_e32 v58, 0xbfb8aa3b, v55
	v_exp_f32_e32 v58, v58
	v_mul_f32_e32 v59, 0xbfb8aa3b, v56
	v_exp_f32_e32 v59, v59
	v_cvt_pk_bf16_f32 v50, v50, v51
	v_add_f32_e32 v58, 1.0, v58
	v_rcp_f32_e32 v69, v58
	v_add_f32_e32 v59, 1.0, v59
	v_mul_f32_e32 v58, 0xbfb8aa3b, v52
	v_exp_f32_e32 v58, v58
	v_pk_mul_f32 v[54:55], v[54:55], v[68:69]
	v_add_f32_e32 v58, 1.0, v58
	v_pk_mul_f32 v[54:55], v[62:63], v[54:55]
	v_rcp_f32_e32 v62, v59
	v_mul_f32_e32 v59, 0xbfb8aa3b, v53
	v_exp_f32_e32 v59, v59
	v_rcp_f32_e32 v58, v58
	v_add_f32_e32 v59, 1.0, v59
	v_rcp_f32_e32 v59, v59
	s_nop 0
	v_pk_mul_f32 v[52:53], v[52:53], v[58:59]
	v_mul_f32_e32 v58, 0xbfb8aa3b, v57
	v_exp_f32_e32 v58, v58
	v_pk_mul_f32 v[52:53], v[60:61], v[52:53]
	v_add_f32_e32 v58, 1.0, v58
	v_rcp_f32_e32 v63, v58
	v_cvt_pk_bf16_f32 v51, v52, v53
	v_cvt_pk_bf16_f32 v52, v54, v55
	v_mad_i64_i32 v[54:55], s[0:1], v184, s35, v[130:131]
	v_pk_mul_f32 v[56:57], v[56:57], v[62:63]
	s_nop 0
	v_pk_mul_f32 v[56:57], v[64:65], v[56:57]
	s_nop 0
	v_cvt_pk_bf16_f32 v53, v56, v57
	global_store_dwordx4 v[54:55], v[50:53], off
	s_nop 1
	v_mul_f32_e32 v51, 0xbfb8aa3b, v38
	v_exp_f32_e32 v51, v51
	v_mul_f32_e32 v50, 0xbfb8aa3b, v34
	v_exp_f32_e32 v50, v50
	v_add_f32_e32 v51, 1.0, v51
	v_rcp_f32_e32 v52, v51
	v_mul_f32_e32 v51, 0xbfb8aa3b, v35
	v_exp_f32_e32 v51, v51
	v_add_f32_e32 v50, 1.0, v50
	v_rcp_f32_e32 v50, v50
	v_add_f32_e32 v51, 1.0, v51
	v_rcp_f32_e32 v51, v51
; #define PG8_WAIT_V(n) asm volatile("s_waitcnt vmcnt(" #n ")" ::: "memory")
; #define PG8_BAR __builtin_amdgcn_s_barrier()
; template <class Epi>
; DEVI void gemm_phase(LAS unsigned char* lds, const Gemm g, const Epi& E) {
;     ...
;         if (!has_next) break;
; #pragma unroll
;         for (int a = 0; a < 2; ++a)
; #pragma unroll
;             for (int b = 0; b < 2; ++b)
; #pragma unroll
;                 for (int m = 0; m < 4; ++m)
; #pragma unroll
;                     for (int n = 0; n < 2; ++n) acc[a][b][m][n] = (f32x4){0.f, 0.f, 0.f, 0.f};
;         cur = nxt; cA = nA; cB = nB; ++ui;
;     }
;     PG8_WAIT_V(0);
;     if (wr == 0) PG8_BAR;
;     PG8_BAR;
	s_nop 0
	v_pk_mul_f32 v[34:35], v[34:35], v[50:51]
	s_nop 0
	v_pk_mul_f32 v[34:35], v[42:43], v[34:35]
	v_mul_f32_e32 v42, 0xbfb8aa3b, v39
	v_exp_f32_e32 v42, v42
	v_mul_f32_e32 v43, 0xbfb8aa3b, v40
	v_exp_f32_e32 v43, v43
	v_cvt_pk_bf16_f32 v34, v34, v35
	v_add_f32_e32 v42, 1.0, v42
	v_rcp_f32_e32 v53, v42
	v_add_f32_e32 v43, 1.0, v43
	v_mul_f32_e32 v42, 0xbfb8aa3b, v36
	v_exp_f32_e32 v42, v42
	v_pk_mul_f32 v[38:39], v[38:39], v[52:53]
	v_add_f32_e32 v42, 1.0, v42
	v_pk_mul_f32 v[38:39], v[46:47], v[38:39]
	v_rcp_f32_e32 v46, v43
	v_mul_f32_e32 v43, 0xbfb8aa3b, v37
	v_exp_f32_e32 v43, v43
	v_rcp_f32_e32 v42, v42
	v_add_f32_e32 v43, 1.0, v43
	v_rcp_f32_e32 v43, v43
	s_nop 0
	v_pk_mul_f32 v[36:37], v[36:37], v[42:43]
	v_mul_f32_e32 v42, 0xbfb8aa3b, v41
	v_exp_f32_e32 v42, v42
	v_pk_mul_f32 v[36:37], v[44:45], v[36:37]
	v_add_f32_e32 v42, 1.0, v42
	v_rcp_f32_e32 v47, v42
	v_cvt_pk_bf16_f32 v35, v36, v37
	v_cvt_pk_bf16_f32 v36, v38, v39
	v_mad_i64_i32 v[38:39], s[0:1], v182, s35, v[130:131]
	v_pk_mul_f32 v[40:41], v[40:41], v[46:47]
	s_nop 0
	v_pk_mul_f32 v[40:41], v[48:49], v[40:41]
	s_nop 0
	v_cvt_pk_bf16_f32 v37, v40, v41
	global_store_dwordx4 v[38:39], v[34:37], off
	s_nop 1
	v_mul_f32_e32 v35, 0xbfb8aa3b, v22
	v_exp_f32_e32 v35, v35
	v_mul_f32_e32 v34, 0xbfb8aa3b, v18
	v_exp_f32_e32 v34, v34
	v_add_f32_e32 v35, 1.0, v35
	v_rcp_f32_e32 v36, v35
	v_mul_f32_e32 v35, 0xbfb8aa3b, v19
	v_exp_f32_e32 v35, v35
	v_add_f32_e32 v34, 1.0, v34
	v_rcp_f32_e32 v34, v34
	v_add_f32_e32 v35, 1.0, v35
	v_rcp_f32_e32 v35, v35
	s_nop 0
	v_pk_mul_f32 v[18:19], v[18:19], v[34:35]
	s_nop 0
	v_pk_mul_f32 v[18:19], v[26:27], v[18:19]
	v_mul_f32_e32 v26, 0xbfb8aa3b, v23
	v_exp_f32_e32 v26, v26
	v_mul_f32_e32 v27, 0xbfb8aa3b, v24
	v_exp_f32_e32 v27, v27
	v_cvt_pk_bf16_f32 v18, v18, v19
	v_add_f32_e32 v26, 1.0, v26
	v_rcp_f32_e32 v37, v26
	v_add_f32_e32 v27, 1.0, v27
	v_mul_f32_e32 v26, 0xbfb8aa3b, v20
	v_exp_f32_e32 v26, v26
	v_pk_mul_f32 v[22:23], v[22:23], v[36:37]
	v_add_f32_e32 v26, 1.0, v26
	v_pk_mul_f32 v[22:23], v[30:31], v[22:23]
	v_rcp_f32_e32 v30, v27
	v_mul_f32_e32 v27, 0xbfb8aa3b, v21
	v_exp_f32_e32 v27, v27
	v_rcp_f32_e32 v26, v26
	v_add_f32_e32 v27, 1.0, v27
	v_rcp_f32_e32 v27, v27
	s_nop 0
	v_pk_mul_f32 v[20:21], v[20:21], v[26:27]
	v_mul_f32_e32 v26, 0xbfb8aa3b, v25
	v_exp_f32_e32 v26, v26
	v_pk_mul_f32 v[20:21], v[28:29], v[20:21]
	v_add_f32_e32 v26, 1.0, v26
	v_rcp_f32_e32 v31, v26
	v_cvt_pk_bf16_f32 v19, v20, v21
	v_cvt_pk_bf16_f32 v20, v22, v23
	v_mad_i64_i32 v[22:23], s[0:1], v180, s35, v[130:131]
	v_pk_mul_f32 v[24:25], v[24:25], v[30:31]
	s_nop 0
	v_pk_mul_f32 v[24:25], v[32:33], v[24:25]
	s_nop 0
	v_cvt_pk_bf16_f32 v21, v24, v25
	global_store_dwordx4 v[22:23], v[18:21], off
	s_nop 1
	v_mul_f32_e32 v19, 0xbfb8aa3b, v4
	v_exp_f32_e32 v19, v19
	v_mul_f32_e32 v18, 0xbfb8aa3b, v0
	v_exp_f32_e32 v18, v18
	v_add_f32_e32 v19, 1.0, v19
	v_rcp_f32_e32 v20, v19
	v_mul_f32_e32 v19, 0xbfb8aa3b, v1
	v_exp_f32_e32 v19, v19
	v_add_f32_e32 v18, 1.0, v18
	v_rcp_f32_e32 v18, v18
	v_add_f32_e32 v19, 1.0, v19
	v_rcp_f32_e32 v19, v19
	s_nop 0
	v_pk_mul_f32 v[0:1], v[0:1], v[18:19]
	s_nop 0
	v_pk_mul_f32 v[0:1], v[10:11], v[0:1]
	v_mul_f32_e32 v10, 0xbfb8aa3b, v5
	v_exp_f32_e32 v10, v10
	v_mul_f32_e32 v11, 0xbfb8aa3b, v6
	v_exp_f32_e32 v11, v11
	v_cvt_pk_bf16_f32 v0, v0, v1
	v_add_f32_e32 v10, 1.0, v10
	v_rcp_f32_e32 v21, v10
	v_add_f32_e32 v11, 1.0, v11
	v_mul_f32_e32 v10, 0xbfb8aa3b, v2
	v_exp_f32_e32 v10, v10
	v_pk_mul_f32 v[4:5], v[4:5], v[20:21]
	v_add_f32_e32 v10, 1.0, v10
	v_pk_mul_f32 v[4:5], v[14:15], v[4:5]
	v_rcp_f32_e32 v14, v11
	v_mul_f32_e32 v11, 0xbfb8aa3b, v3
	v_exp_f32_e32 v11, v11
	v_rcp_f32_e32 v10, v10
	v_add_f32_e32 v11, 1.0, v11
	v_rcp_f32_e32 v11, v11
	s_nop 0
	v_pk_mul_f32 v[2:3], v[2:3], v[10:11]
	v_mul_f32_e32 v10, 0xbfb8aa3b, v7
	v_exp_f32_e32 v10, v10
	v_pk_mul_f32 v[2:3], v[12:13], v[2:3]
	v_add_f32_e32 v10, 1.0, v10
	v_rcp_f32_e32 v15, v10
	v_cvt_pk_bf16_f32 v1, v2, v3
	v_cvt_pk_bf16_f32 v2, v4, v5
	v_mad_i64_i32 v[4:5], s[0:1], v178, s35, v[130:131]
	v_pk_mul_f32 v[6:7], v[6:7], v[14:15]
	s_nop 0
	v_pk_mul_f32 v[6:7], v[16:17], v[6:7]
	s_nop 0
	v_cvt_pk_bf16_f32 v3, v6, v7
	global_store_dwordx4 v[4:5], v[0:3], off
	s_cbranch_vccz .LBB0_1669
	s_waitcnt vmcnt(0)
	s_cmpk_gt_u32 s66, 0xff
	s_cbranch_scc1 .LBB0_1676
	s_barrier
